# GEMM units start from SrcC=0 first K-tile (no accumulator zeroing, no VMEM drain); prep silu(c) fill unrolled with all loads in flight
# speedup vs baseline: 1.0077x; 1.0031x over previous
.LBB0_49:
	s_ashr_i32 s35, s34, 31
	s_lshl_b64 s[26:27], s[34:35], 20
	s_add_u32 s42, s16, s26
	s_addc_u32 s43, s17, s27
	s_and_b64 s[26:27], s[38:39], exec
	s_cselect_b32 s35, s43, s11
	s_cselect_b32 s52, s42, s10
	s_ashr_i32 s21, s20, 31
	s_lshl_b64 s[26:27], s[20:21], 20
	s_add_u32 s26, s2, s26
	s_addc_u32 s27, s15, s27
	s_and_b64 s[54:55], s[38:39], exec
	s_cselect_b32 s21, s27, s45
	s_cselect_b32 s53, s26, s44
	s_add_u32 vcc_lo, s10, 0x80080
	s_addc_u32 vcc_hi, s11, 0
	s_add_u32 s54, s44, 0x100
	s_addc_u32 s55, s45, 0
	s_mov_b32 s56, -2
	s_add_u32 s10, vcc_lo, 0xfff80080
	s_addc_u32 s11, vcc_hi, -1
	s_add_i32 s57, 0, 0x10000
	s_cmp_eq_u32 s56, 28
	s_cselect_b32 s11, s35, s11
	s_cselect_b32 s10, s52, s10
	v_add_u32_e32 v140, s57, v143
	s_cselect_b32 s45, s21, s55
	s_cselect_b32 s44, s53, s54
	s_add_i32 s60, 0, 0x14000
	ds_read_b128 v[146:149], v140
	ds_read_b128 v[150:153], v140 offset:1024
	ds_read_b128 v[154:157], v140 offset:2048
	ds_read_b128 v[158:161], v140 offset:3072
	v_add_u32_e32 v140, s60, v143
	ds_read_b128 v[162:165], v140
	ds_read_b128 v[166:169], v140 offset:1024
	ds_read_b128 v[170:173], v140 offset:2048
	ds_read_b128 v[174:177], v140 offset:3072
	v_lshl_add_u64 v[140:141], vcc, 0, v[136:137]
	s_add_i32 m0, s23, 0xc000
	ds_read_b128 v[178:181], v145
	ds_read_b128 v[182:185], v145 offset:1024
	ds_read_b128 v[190:193], v145 offset:2048
	ds_read_b128 v[200:203], v145 offset:3072
	ds_read_b128 v[204:207], v145 offset:4096
	ds_read_b128 v[208:211], v145 offset:5120
	ds_read_b128 v[212:215], v145 offset:6144
	ds_read_b128 v[216:219], v145 offset:7168
	global_load_lds_dwordx4 v[140:141], off
	v_lshl_add_u64 v[140:141], vcc, 0, v[138:139]
	s_add_i32 m0, s23, 0xe000
	s_nop 0
	global_load_lds_dwordx4 v[140:141], off
	s_waitcnt vmcnt(8)
	s_waitcnt lgkmcnt(0)
	s_barrier
	s_setprio 1
	s_waitcnt lgkmcnt(0)
	v_mfma_f32_16x16x32_bf16 v[126:129], v[146:149], v[178:181], 0
	v_mfma_f32_16x16x32_bf16 v[122:125], v[154:157], v[178:181], 0
	v_mfma_f32_16x16x32_bf16 v[118:121], v[146:149], v[190:193], 0
	v_mfma_f32_16x16x32_bf16 v[110:113], v[154:157], v[190:193], 0
	v_mfma_f32_16x16x32_bf16 v[102:105], v[146:149], v[204:207], 0
	v_mfma_f32_16x16x32_bf16 v[94:97], v[154:157], v[204:207], 0
	v_mfma_f32_16x16x32_bf16 v[86:89], v[146:149], v[212:215], 0
	v_mfma_f32_16x16x32_bf16 v[78:81], v[154:157], v[212:215], 0
	v_mfma_f32_16x16x32_bf16 v[126:129], v[150:153], v[182:185], v[126:129]
	v_mfma_f32_16x16x32_bf16 v[122:125], v[158:161], v[182:185], v[122:125]
	v_mfma_f32_16x16x32_bf16 v[118:121], v[150:153], v[200:203], v[118:121]
	v_mfma_f32_16x16x32_bf16 v[110:113], v[158:161], v[200:203], v[110:113]
	v_mfma_f32_16x16x32_bf16 v[102:105], v[150:153], v[208:211], v[102:105]
	v_mfma_f32_16x16x32_bf16 v[94:97], v[158:161], v[208:211], v[94:97]
	v_mfma_f32_16x16x32_bf16 v[86:89], v[150:153], v[216:219], v[86:89]
	v_mfma_f32_16x16x32_bf16 v[78:81], v[158:161], v[216:219], v[78:81]
	s_setprio 0
	s_setprio 1
	v_mfma_f32_16x16x32_bf16 v[114:117], v[162:165], v[178:181], 0
	v_mfma_f32_16x16x32_bf16 v[106:109], v[170:173], v[178:181], 0
	v_mfma_f32_16x16x32_bf16 v[98:101], v[162:165], v[190:193], 0
	v_mfma_f32_16x16x32_bf16 v[90:93], v[170:173], v[190:193], 0
	v_mfma_f32_16x16x32_bf16 v[82:85], v[162:165], v[204:207], 0
	v_mfma_f32_16x16x32_bf16 v[74:77], v[170:173], v[204:207], 0
	v_mfma_f32_16x16x32_bf16 v[70:73], v[162:165], v[212:215], 0
	v_mfma_f32_16x16x32_bf16 v[66:69], v[170:173], v[212:215], 0
	v_mfma_f32_16x16x32_bf16 v[114:117], v[166:169], v[182:185], v[114:117]
	v_mfma_f32_16x16x32_bf16 v[106:109], v[174:177], v[182:185], v[106:109]
	v_mfma_f32_16x16x32_bf16 v[98:101], v[166:169], v[200:203], v[98:101]
	v_mfma_f32_16x16x32_bf16 v[90:93], v[174:177], v[200:203], v[90:93]
	v_mfma_f32_16x16x32_bf16 v[82:85], v[166:169], v[208:211], v[82:85]
	v_mfma_f32_16x16x32_bf16 v[74:77], v[174:177], v[208:211], v[74:77]
	v_mfma_f32_16x16x32_bf16 v[70:73], v[166:169], v[216:219], v[70:73]
	v_mfma_f32_16x16x32_bf16 v[66:69], v[174:177], v[216:219], v[66:69]
	s_setprio 0
	s_barrier
	s_add_i32 s57, s57, s22
	v_lshl_add_u64 v[140:141], s[44:45], 0, v[0:1]
	s_mov_b32 m0, s57
	ds_read_b128 v[178:181], v145 offset:16384
	ds_read_b128 v[182:185], v145 offset:17408
	ds_read_b128 v[190:193], v145 offset:18432
	ds_read_b128 v[200:203], v145 offset:19456
	ds_read_b128 v[204:207], v145 offset:20480
	ds_read_b128 v[208:211], v145 offset:21504
	ds_read_b128 v[212:215], v145 offset:22528
	ds_read_b128 v[216:219], v145 offset:23552
	global_load_lds_dwordx4 v[140:141], off
	s_add_i32 m0, s57, 0x2000
	s_add_u32 s58, s44, 0x80000
	v_lshl_add_u64 v[220:221], s[44:45], 0, v[130:131]
	s_addc_u32 s59, s45, 0
	s_add_i32 s57, s60, s22
	global_load_lds_dwordx4 v[220:221], off
	v_lshl_add_u64 v[222:223], s[58:59], 0, v[0:1]
	s_mov_b32 m0, s57
	v_lshl_add_u64 v[224:225], s[10:11], 0, v[132:133]
	global_load_lds_dwordx4 v[222:223], off
	v_lshl_add_u64 v[222:223], s[58:59], 0, v[130:131]
	s_add_i32 m0, s57, 0x2000
	s_nop 0
	global_load_lds_dwordx4 v[222:223], off
	v_lshl_add_u64 v[222:223], s[10:11], 0, v[134:135]
	s_mov_b32 m0, s23
	s_nop 0
	global_load_lds_dwordx4 v[222:223], off
	s_mov_b32 m0, s41
	s_nop 0
	global_load_lds_dwordx4 v[224:225], off
	s_waitcnt vmcnt(8)
	s_waitcnt lgkmcnt(0)
	s_barrier
	s_setprio 1
	s_waitcnt lgkmcnt(0)
	v_mfma_f32_16x16x32_bf16 v[62:65], v[146:149], v[178:181], 0
	v_mfma_f32_16x16x32_bf16 v[58:61], v[154:157], v[178:181], 0
	v_mfma_f32_16x16x32_bf16 v[54:57], v[146:149], v[190:193], 0
	v_mfma_f32_16x16x32_bf16 v[46:49], v[154:157], v[190:193], 0
	v_mfma_f32_16x16x32_bf16 v[38:41], v[146:149], v[204:207], 0
	v_mfma_f32_16x16x32_bf16 v[30:33], v[154:157], v[204:207], 0
	v_mfma_f32_16x16x32_bf16 v[22:25], v[146:149], v[212:215], 0
	v_mfma_f32_16x16x32_bf16 v[14:17], v[154:157], v[212:215], 0
	v_mfma_f32_16x16x32_bf16 v[62:65], v[150:153], v[182:185], v[62:65]
	v_mfma_f32_16x16x32_bf16 v[58:61], v[158:161], v[182:185], v[58:61]
	v_mfma_f32_16x16x32_bf16 v[54:57], v[150:153], v[200:203], v[54:57]
	v_mfma_f32_16x16x32_bf16 v[46:49], v[158:161], v[200:203], v[46:49]
	v_mfma_f32_16x16x32_bf16 v[38:41], v[150:153], v[208:211], v[38:41]
	v_mfma_f32_16x16x32_bf16 v[30:33], v[158:161], v[208:211], v[30:33]
	v_mfma_f32_16x16x32_bf16 v[22:25], v[150:153], v[216:219], v[22:25]
	v_mfma_f32_16x16x32_bf16 v[14:17], v[158:161], v[216:219], v[14:17]
	s_setprio 0
	s_setprio 1
	v_mfma_f32_16x16x32_bf16 v[50:53], v[162:165], v[178:181], 0
	v_mfma_f32_16x16x32_bf16 v[42:45], v[170:173], v[178:181], 0
	v_mfma_f32_16x16x32_bf16 v[34:37], v[162:165], v[190:193], 0
	v_mfma_f32_16x16x32_bf16 v[26:29], v[170:173], v[190:193], 0
	v_mfma_f32_16x16x32_bf16 v[18:21], v[162:165], v[204:207], 0
	v_mfma_f32_16x16x32_bf16 v[10:13], v[170:173], v[204:207], 0
	v_mfma_f32_16x16x32_bf16 v[6:9], v[162:165], v[212:215], 0
	v_mfma_f32_16x16x32_bf16 v[2:5], v[170:173], v[212:215], 0
	v_mfma_f32_16x16x32_bf16 v[50:53], v[166:169], v[182:185], v[50:53]
	v_mfma_f32_16x16x32_bf16 v[42:45], v[174:177], v[182:185], v[42:45]
	v_mfma_f32_16x16x32_bf16 v[34:37], v[166:169], v[200:203], v[34:37]
	v_mfma_f32_16x16x32_bf16 v[26:29], v[174:177], v[200:203], v[26:29]
	v_mfma_f32_16x16x32_bf16 v[18:21], v[166:169], v[208:211], v[18:21]
	v_mfma_f32_16x16x32_bf16 v[10:13], v[174:177], v[208:211], v[10:13]
	v_mfma_f32_16x16x32_bf16 v[6:9], v[166:169], v[216:219], v[6:9]
	v_mfma_f32_16x16x32_bf16 v[2:5], v[174:177], v[216:219], v[2:5]
	s_setprio 0
	s_barrier
	s_branch .Lg50_mid

.LBB0_72:
	s_ashr_i32 s35, s34, 31
	s_lshl_b64 s[42:43], s[34:35], 19
	v_readlane_b32 s44, v255, 8
	v_readlane_b32 s45, v255, 9
	s_add_u32 s42, s44, s42
	s_addc_u32 s43, s45, s43
	s_and_b64 s[44:45], s[38:39], exec
	s_cselect_b32 s35, s43, s11
	s_cselect_b32 s52, s42, s10
	s_ashr_i32 s21, s20, 31
	s_lshl_b64 s[44:45], s[20:21], 19
	s_add_u32 s44, s2, s44
	s_addc_u32 s45, s15, s45
	s_and_b64 s[54:55], s[38:39], exec
	s_cselect_b32 s21, s45, s27
	s_cselect_b32 s53, s44, s26
	s_add_u32 vcc_lo, s10, 0x40080
	s_addc_u32 vcc_hi, s11, 0
	s_add_u32 s54, s26, 0x100
	s_addc_u32 s55, s27, 0
	s_mov_b32 s56, -2
	s_add_u32 s10, vcc_lo, 0xfffc0080
	s_addc_u32 s11, vcc_hi, -1
	s_add_i32 s57, 0, 0x10000
	s_cmp_eq_u32 s56, 12
	s_cselect_b32 s11, s35, s11
	s_cselect_b32 s10, s52, s10
	v_add_u32_e32 v140, s57, v143
	s_cselect_b32 s27, s21, s55
	s_cselect_b32 s26, s53, s54
	s_add_i32 s60, 0, 0x14000
	ds_read_b128 v[146:149], v140
	ds_read_b128 v[150:153], v140 offset:1024
	ds_read_b128 v[154:157], v140 offset:2048
	ds_read_b128 v[158:161], v140 offset:3072
	v_add_u32_e32 v140, s60, v143
	ds_read_b128 v[162:165], v140
	ds_read_b128 v[166:169], v140 offset:1024
	ds_read_b128 v[170:173], v140 offset:2048
	ds_read_b128 v[174:177], v140 offset:3072
	v_lshl_add_u64 v[140:141], vcc, 0, v[136:137]
	s_add_i32 m0, s23, 0xc000
	ds_read_b128 v[178:181], v145
	ds_read_b128 v[182:185], v145 offset:1024
	ds_read_b128 v[200:203], v145 offset:2048
	ds_read_b128 v[204:207], v145 offset:3072
	ds_read_b128 v[208:211], v145 offset:4096
	ds_read_b128 v[212:215], v145 offset:5120
	ds_read_b128 v[216:219], v145 offset:6144
	ds_read_b128 v[220:223], v145 offset:7168
	global_load_lds_dwordx4 v[140:141], off
	v_lshl_add_u64 v[140:141], vcc, 0, v[138:139]
	s_add_i32 m0, s23, 0xe000
	s_nop 0
	global_load_lds_dwordx4 v[140:141], off
	s_waitcnt vmcnt(8)
	s_waitcnt lgkmcnt(0)
	s_barrier
	s_setprio 1
	s_waitcnt lgkmcnt(0)
	v_mfma_f32_16x16x32_bf16 v[126:129], v[146:149], v[178:181], 0
	v_mfma_f32_16x16x32_bf16 v[122:125], v[154:157], v[178:181], 0
	v_mfma_f32_16x16x32_bf16 v[118:121], v[146:149], v[200:203], 0
	v_mfma_f32_16x16x32_bf16 v[110:113], v[154:157], v[200:203], 0
	v_mfma_f32_16x16x32_bf16 v[102:105], v[146:149], v[208:211], 0
	v_mfma_f32_16x16x32_bf16 v[94:97], v[154:157], v[208:211], 0
	v_mfma_f32_16x16x32_bf16 v[86:89], v[146:149], v[216:219], 0
	v_mfma_f32_16x16x32_bf16 v[78:81], v[154:157], v[216:219], 0
	v_mfma_f32_16x16x32_bf16 v[126:129], v[150:153], v[182:185], v[126:129]
	v_mfma_f32_16x16x32_bf16 v[122:125], v[158:161], v[182:185], v[122:125]
	v_mfma_f32_16x16x32_bf16 v[118:121], v[150:153], v[204:207], v[118:121]
	v_mfma_f32_16x16x32_bf16 v[110:113], v[158:161], v[204:207], v[110:113]
	v_mfma_f32_16x16x32_bf16 v[102:105], v[150:153], v[212:215], v[102:105]
	v_mfma_f32_16x16x32_bf16 v[94:97], v[158:161], v[212:215], v[94:97]
	v_mfma_f32_16x16x32_bf16 v[86:89], v[150:153], v[220:223], v[86:89]
	v_mfma_f32_16x16x32_bf16 v[78:81], v[158:161], v[220:223], v[78:81]
	s_setprio 0
	s_setprio 1
	v_mfma_f32_16x16x32_bf16 v[114:117], v[162:165], v[178:181], 0
	v_mfma_f32_16x16x32_bf16 v[106:109], v[170:173], v[178:181], 0
	v_mfma_f32_16x16x32_bf16 v[98:101], v[162:165], v[200:203], 0
	v_mfma_f32_16x16x32_bf16 v[90:93], v[170:173], v[200:203], 0
	v_mfma_f32_16x16x32_bf16 v[82:85], v[162:165], v[208:211], 0
	v_mfma_f32_16x16x32_bf16 v[74:77], v[170:173], v[208:211], 0
	v_mfma_f32_16x16x32_bf16 v[70:73], v[162:165], v[216:219], 0
	v_mfma_f32_16x16x32_bf16 v[66:69], v[170:173], v[216:219], 0
	v_mfma_f32_16x16x32_bf16 v[114:117], v[166:169], v[182:185], v[114:117]
	v_mfma_f32_16x16x32_bf16 v[106:109], v[174:177], v[182:185], v[106:109]
	v_mfma_f32_16x16x32_bf16 v[98:101], v[166:169], v[204:207], v[98:101]
	v_mfma_f32_16x16x32_bf16 v[90:93], v[174:177], v[204:207], v[90:93]
	v_mfma_f32_16x16x32_bf16 v[82:85], v[166:169], v[212:215], v[82:85]
	v_mfma_f32_16x16x32_bf16 v[74:77], v[174:177], v[212:215], v[74:77]
	v_mfma_f32_16x16x32_bf16 v[70:73], v[166:169], v[220:223], v[70:73]
	v_mfma_f32_16x16x32_bf16 v[66:69], v[174:177], v[220:223], v[66:69]
	s_setprio 0
	s_barrier
	s_add_i32 s57, s57, s22
	v_lshl_add_u64 v[140:141], s[26:27], 0, v[0:1]
	s_mov_b32 m0, s57
	ds_read_b128 v[178:181], v145 offset:16384
	ds_read_b128 v[182:185], v145 offset:17408
	ds_read_b128 v[200:203], v145 offset:18432
	ds_read_b128 v[204:207], v145 offset:19456
	ds_read_b128 v[208:211], v145 offset:20480
	ds_read_b128 v[212:215], v145 offset:21504
	ds_read_b128 v[216:219], v145 offset:22528
	ds_read_b128 v[220:223], v145 offset:23552
	global_load_lds_dwordx4 v[140:141], off
	s_add_i32 m0, s57, 0x2000
	s_add_u32 s58, s26, 0x40000
	v_lshl_add_u64 v[190:191], s[26:27], 0, v[130:131]
	s_addc_u32 s59, s27, 0
	s_add_i32 s57, s60, s22
	global_load_lds_dwordx4 v[190:191], off
	v_lshl_add_u64 v[192:193], s[58:59], 0, v[0:1]
	s_mov_b32 m0, s57
	v_lshl_add_u64 v[224:225], s[10:11], 0, v[132:133]
	global_load_lds_dwordx4 v[192:193], off
	v_lshl_add_u64 v[192:193], s[58:59], 0, v[130:131]
	s_add_i32 m0, s57, 0x2000
	s_nop 0
	global_load_lds_dwordx4 v[192:193], off
	v_lshl_add_u64 v[192:193], s[10:11], 0, v[134:135]
	s_mov_b32 m0, s23
	s_nop 0
	global_load_lds_dwordx4 v[192:193], off
	s_mov_b32 m0, s40
	s_nop 0
	global_load_lds_dwordx4 v[224:225], off
	s_waitcnt vmcnt(8)
	s_waitcnt lgkmcnt(0)
	s_barrier
	s_setprio 1
	s_waitcnt lgkmcnt(0)
	v_mfma_f32_16x16x32_bf16 v[62:65], v[146:149], v[178:181], 0
	v_mfma_f32_16x16x32_bf16 v[58:61], v[154:157], v[178:181], 0
	v_mfma_f32_16x16x32_bf16 v[54:57], v[146:149], v[200:203], 0
	v_mfma_f32_16x16x32_bf16 v[46:49], v[154:157], v[200:203], 0
	v_mfma_f32_16x16x32_bf16 v[38:41], v[146:149], v[208:211], 0
	v_mfma_f32_16x16x32_bf16 v[30:33], v[154:157], v[208:211], 0
	v_mfma_f32_16x16x32_bf16 v[22:25], v[146:149], v[216:219], 0
	v_mfma_f32_16x16x32_bf16 v[14:17], v[154:157], v[216:219], 0
	v_mfma_f32_16x16x32_bf16 v[62:65], v[150:153], v[182:185], v[62:65]
	v_mfma_f32_16x16x32_bf16 v[58:61], v[158:161], v[182:185], v[58:61]
	v_mfma_f32_16x16x32_bf16 v[54:57], v[150:153], v[204:207], v[54:57]
	v_mfma_f32_16x16x32_bf16 v[46:49], v[158:161], v[204:207], v[46:49]
	v_mfma_f32_16x16x32_bf16 v[38:41], v[150:153], v[212:215], v[38:41]
	v_mfma_f32_16x16x32_bf16 v[30:33], v[158:161], v[212:215], v[30:33]
	v_mfma_f32_16x16x32_bf16 v[22:25], v[150:153], v[220:223], v[22:25]
	v_mfma_f32_16x16x32_bf16 v[14:17], v[158:161], v[220:223], v[14:17]
	s_setprio 0
	s_setprio 1
	v_mfma_f32_16x16x32_bf16 v[50:53], v[162:165], v[178:181], 0
	v_mfma_f32_16x16x32_bf16 v[42:45], v[170:173], v[178:181], 0
	v_mfma_f32_16x16x32_bf16 v[34:37], v[162:165], v[200:203], 0
	v_mfma_f32_16x16x32_bf16 v[26:29], v[170:173], v[200:203], 0
	v_mfma_f32_16x16x32_bf16 v[18:21], v[162:165], v[208:211], 0
	v_mfma_f32_16x16x32_bf16 v[10:13], v[170:173], v[208:211], 0
	v_mfma_f32_16x16x32_bf16 v[6:9], v[162:165], v[216:219], 0
	v_mfma_f32_16x16x32_bf16 v[2:5], v[170:173], v[216:219], 0
	v_mfma_f32_16x16x32_bf16 v[50:53], v[166:169], v[182:185], v[50:53]
	v_mfma_f32_16x16x32_bf16 v[42:45], v[174:177], v[182:185], v[42:45]
	v_mfma_f32_16x16x32_bf16 v[34:37], v[166:169], v[204:207], v[34:37]
	v_mfma_f32_16x16x32_bf16 v[26:29], v[174:177], v[204:207], v[26:29]
	v_mfma_f32_16x16x32_bf16 v[18:21], v[166:169], v[212:215], v[18:21]
	v_mfma_f32_16x16x32_bf16 v[10:13], v[174:177], v[212:215], v[10:13]
	v_mfma_f32_16x16x32_bf16 v[6:9], v[166:169], v[220:223], v[6:9]
	v_mfma_f32_16x16x32_bf16 v[2:5], v[174:177], v[220:223], v[2:5]
	s_setprio 0
	s_barrier
	s_branch .Lg73_mid

.LBB0_151:
	s_mov_b64 s[6:7], 0x1000
	global_load_dword v108, v[2:3], off
	global_load_dword v109, v[2:3], off offset:2048
	v_lshl_add_u64 v[2:3], v[2:3], 0, s[6:7]
	global_load_dword v110, v[2:3], off
	global_load_dword v111, v[2:3], off offset:2048
	v_lshl_add_u64 v[2:3], v[2:3], 0, s[6:7]
	global_load_dword v112, v[2:3], off
	global_load_dword v113, v[2:3], off offset:2048
	v_lshl_add_u64 v[2:3], v[2:3], 0, s[6:7]
	global_load_dword v114, v[2:3], off
	global_load_dword v115, v[2:3], off offset:2048
	v_lshl_add_u64 v[2:3], v[2:3], 0, s[6:7]
	global_load_dword v116, v[2:3], off
	global_load_dword v117, v[2:3], off offset:2048
	v_lshl_add_u64 v[2:3], v[2:3], 0, s[6:7]
	global_load_dword v118, v[2:3], off
	global_load_dword v119, v[2:3], off offset:2048
	v_lshl_add_u64 v[2:3], v[2:3], 0, s[6:7]
	global_load_dword v120, v[2:3], off
	global_load_dword v121, v[2:3], off offset:2048
	v_lshl_add_u64 v[2:3], v[2:3], 0, s[6:7]
	global_load_dword v122, v[2:3], off
	global_load_dword v123, v[2:3], off offset:2048
	s_waitcnt vmcnt(15)
	v_mul_f32_e32 v6, 0xbfb8aa3b, v108
	v_exp_f32_e32 v6, v6
	s_nop 0
	v_add_f32_e32 v6, 1.0, v6
	v_div_scale_f32 v7, s[6:7], v6, v6, v108
	v_rcp_f32_e32 v8, v7
	v_div_scale_f32 v9, vcc, v108, v6, v108
	v_fma_f32 v10, -v7, v8, 1.0
	v_fmac_f32_e32 v8, v10, v8
	v_mul_f32_e32 v10, v9, v8
	v_fma_f32 v11, -v7, v10, v9
	v_fmac_f32_e32 v10, v11, v8
	v_fma_f32 v7, -v7, v10, v9
	v_div_fmas_f32 v7, v7, v8, v10
	v_div_fixup_f32 v5, v7, v6, v108
	ds_write_b32 v4, v5
	s_waitcnt vmcnt(14)
	v_mul_f32_e32 v6, 0xbfb8aa3b, v109
	v_exp_f32_e32 v6, v6
	s_nop 0
	v_add_f32_e32 v6, 1.0, v6
	v_div_scale_f32 v7, s[6:7], v6, v6, v109
	v_rcp_f32_e32 v8, v7
	v_div_scale_f32 v9, vcc, v109, v6, v109
	v_fma_f32 v10, -v7, v8, 1.0
	v_fmac_f32_e32 v8, v10, v8
	v_mul_f32_e32 v10, v9, v8
	v_fma_f32 v11, -v7, v10, v9
	v_fmac_f32_e32 v10, v11, v8
	v_fma_f32 v7, -v7, v10, v9
	v_div_fmas_f32 v7, v7, v8, v10
	v_div_fixup_f32 v5, v7, v6, v109
	ds_write_b32 v4, v5 offset:2048
	s_waitcnt vmcnt(13)
	v_mul_f32_e32 v6, 0xbfb8aa3b, v110
	v_exp_f32_e32 v6, v6
	s_nop 0
	v_add_f32_e32 v6, 1.0, v6
	v_div_scale_f32 v7, s[6:7], v6, v6, v110
	v_rcp_f32_e32 v8, v7
	v_div_scale_f32 v9, vcc, v110, v6, v110
	v_fma_f32 v10, -v7, v8, 1.0
	v_fmac_f32_e32 v8, v10, v8
	v_mul_f32_e32 v10, v9, v8
	v_fma_f32 v11, -v7, v10, v9
	v_fmac_f32_e32 v10, v11, v8
	v_fma_f32 v7, -v7, v10, v9
	v_div_fmas_f32 v7, v7, v8, v10
	v_div_fixup_f32 v5, v7, v6, v110
	ds_write_b32 v4, v5 offset:4096
	s_waitcnt vmcnt(12)
	v_mul_f32_e32 v6, 0xbfb8aa3b, v111
	v_exp_f32_e32 v6, v6
	s_nop 0
	v_add_f32_e32 v6, 1.0, v6
	v_div_scale_f32 v7, s[6:7], v6, v6, v111
	v_rcp_f32_e32 v8, v7
	v_div_scale_f32 v9, vcc, v111, v6, v111
	v_fma_f32 v10, -v7, v8, 1.0
	v_fmac_f32_e32 v8, v10, v8
	v_mul_f32_e32 v10, v9, v8
	v_fma_f32 v11, -v7, v10, v9
	v_fmac_f32_e32 v10, v11, v8
	v_fma_f32 v7, -v7, v10, v9
	v_div_fmas_f32 v7, v7, v8, v10
	v_div_fixup_f32 v5, v7, v6, v111
	ds_write_b32 v4, v5 offset:6144
	s_waitcnt vmcnt(11)
	v_mul_f32_e32 v6, 0xbfb8aa3b, v112
	v_exp_f32_e32 v6, v6
	s_nop 0
	v_add_f32_e32 v6, 1.0, v6
	v_div_scale_f32 v7, s[6:7], v6, v6, v112
	v_rcp_f32_e32 v8, v7
	v_div_scale_f32 v9, vcc, v112, v6, v112
	v_fma_f32 v10, -v7, v8, 1.0
	v_fmac_f32_e32 v8, v10, v8
	v_mul_f32_e32 v10, v9, v8
	v_fma_f32 v11, -v7, v10, v9
	v_fmac_f32_e32 v10, v11, v8
	v_fma_f32 v7, -v7, v10, v9
	v_div_fmas_f32 v7, v7, v8, v10
	v_div_fixup_f32 v5, v7, v6, v112
	ds_write_b32 v4, v5 offset:8192
	s_waitcnt vmcnt(10)
	v_mul_f32_e32 v6, 0xbfb8aa3b, v113
	v_exp_f32_e32 v6, v6
	s_nop 0
	v_add_f32_e32 v6, 1.0, v6
	v_div_scale_f32 v7, s[6:7], v6, v6, v113
	v_rcp_f32_e32 v8, v7
	v_div_scale_f32 v9, vcc, v113, v6, v113
	v_fma_f32 v10, -v7, v8, 1.0
	v_fmac_f32_e32 v8, v10, v8
	v_mul_f32_e32 v10, v9, v8
	v_fma_f32 v11, -v7, v10, v9
	v_fmac_f32_e32 v10, v11, v8
	v_fma_f32 v7, -v7, v10, v9
	v_div_fmas_f32 v7, v7, v8, v10
	v_div_fixup_f32 v5, v7, v6, v113
	ds_write_b32 v4, v5 offset:10240
	s_waitcnt vmcnt(9)
	v_mul_f32_e32 v6, 0xbfb8aa3b, v114
	v_exp_f32_e32 v6, v6
	s_nop 0
	v_add_f32_e32 v6, 1.0, v6
	v_div_scale_f32 v7, s[6:7], v6, v6, v114
	v_rcp_f32_e32 v8, v7
	v_div_scale_f32 v9, vcc, v114, v6, v114
	v_fma_f32 v10, -v7, v8, 1.0
	v_fmac_f32_e32 v8, v10, v8
	v_mul_f32_e32 v10, v9, v8
	v_fma_f32 v11, -v7, v10, v9
	v_fmac_f32_e32 v10, v11, v8
	v_fma_f32 v7, -v7, v10, v9
	v_div_fmas_f32 v7, v7, v8, v10
	v_div_fixup_f32 v5, v7, v6, v114
	ds_write_b32 v4, v5 offset:12288
	s_waitcnt vmcnt(8)
	v_mul_f32_e32 v6, 0xbfb8aa3b, v115
	v_exp_f32_e32 v6, v6
	s_nop 0
	v_add_f32_e32 v6, 1.0, v6
	v_div_scale_f32 v7, s[6:7], v6, v6, v115
	v_rcp_f32_e32 v8, v7
	v_div_scale_f32 v9, vcc, v115, v6, v115
	v_fma_f32 v10, -v7, v8, 1.0
	v_fmac_f32_e32 v8, v10, v8
	v_mul_f32_e32 v10, v9, v8
	v_fma_f32 v11, -v7, v10, v9
	v_fmac_f32_e32 v10, v11, v8
	v_fma_f32 v7, -v7, v10, v9
	v_div_fmas_f32 v7, v7, v8, v10
	v_div_fixup_f32 v5, v7, v6, v115
	ds_write_b32 v4, v5 offset:14336
	s_waitcnt vmcnt(7)
	v_mul_f32_e32 v6, 0xbfb8aa3b, v116
	v_exp_f32_e32 v6, v6
	s_nop 0
	v_add_f32_e32 v6, 1.0, v6
	v_div_scale_f32 v7, s[6:7], v6, v6, v116
	v_rcp_f32_e32 v8, v7
	v_div_scale_f32 v9, vcc, v116, v6, v116
	v_fma_f32 v10, -v7, v8, 1.0
	v_fmac_f32_e32 v8, v10, v8
	v_mul_f32_e32 v10, v9, v8
	v_fma_f32 v11, -v7, v10, v9
	v_fmac_f32_e32 v10, v11, v8
	v_fma_f32 v7, -v7, v10, v9
	v_div_fmas_f32 v7, v7, v8, v10
	v_div_fixup_f32 v5, v7, v6, v116
	ds_write_b32 v4, v5 offset:16384
	s_waitcnt vmcnt(6)
	v_mul_f32_e32 v6, 0xbfb8aa3b, v117
	v_exp_f32_e32 v6, v6
	s_nop 0
	v_add_f32_e32 v6, 1.0, v6
	v_div_scale_f32 v7, s[6:7], v6, v6, v117
	v_rcp_f32_e32 v8, v7
	v_div_scale_f32 v9, vcc, v117, v6, v117
	v_fma_f32 v10, -v7, v8, 1.0
	v_fmac_f32_e32 v8, v10, v8
	v_mul_f32_e32 v10, v9, v8
	v_fma_f32 v11, -v7, v10, v9
	v_fmac_f32_e32 v10, v11, v8
	v_fma_f32 v7, -v7, v10, v9
	v_div_fmas_f32 v7, v7, v8, v10
	v_div_fixup_f32 v5, v7, v6, v117
	ds_write_b32 v4, v5 offset:18432
	s_waitcnt vmcnt(5)
	v_mul_f32_e32 v6, 0xbfb8aa3b, v118
	v_exp_f32_e32 v6, v6
	s_nop 0
	v_add_f32_e32 v6, 1.0, v6
	v_div_scale_f32 v7, s[6:7], v6, v6, v118
	v_rcp_f32_e32 v8, v7
	v_div_scale_f32 v9, vcc, v118, v6, v118
	v_fma_f32 v10, -v7, v8, 1.0
	v_fmac_f32_e32 v8, v10, v8
	v_mul_f32_e32 v10, v9, v8
	v_fma_f32 v11, -v7, v10, v9
	v_fmac_f32_e32 v10, v11, v8
	v_fma_f32 v7, -v7, v10, v9
	v_div_fmas_f32 v7, v7, v8, v10
	v_div_fixup_f32 v5, v7, v6, v118
	ds_write_b32 v4, v5 offset:20480
	s_waitcnt vmcnt(4)
	v_mul_f32_e32 v6, 0xbfb8aa3b, v119
	v_exp_f32_e32 v6, v6
	s_nop 0
	v_add_f32_e32 v6, 1.0, v6
	v_div_scale_f32 v7, s[6:7], v6, v6, v119
	v_rcp_f32_e32 v8, v7
	v_div_scale_f32 v9, vcc, v119, v6, v119
	v_fma_f32 v10, -v7, v8, 1.0
	v_fmac_f32_e32 v8, v10, v8
	v_mul_f32_e32 v10, v9, v8
	v_fma_f32 v11, -v7, v10, v9
	v_fmac_f32_e32 v10, v11, v8
	v_fma_f32 v7, -v7, v10, v9
	v_div_fmas_f32 v7, v7, v8, v10
	v_div_fixup_f32 v5, v7, v6, v119
	ds_write_b32 v4, v5 offset:22528
	s_waitcnt vmcnt(3)
	v_mul_f32_e32 v6, 0xbfb8aa3b, v120
	v_exp_f32_e32 v6, v6
	s_nop 0
	v_add_f32_e32 v6, 1.0, v6
	v_div_scale_f32 v7, s[6:7], v6, v6, v120
	v_rcp_f32_e32 v8, v7
	v_div_scale_f32 v9, vcc, v120, v6, v120
	v_fma_f32 v10, -v7, v8, 1.0
	v_fmac_f32_e32 v8, v10, v8
	v_mul_f32_e32 v10, v9, v8
	v_fma_f32 v11, -v7, v10, v9
	v_fmac_f32_e32 v10, v11, v8
	v_fma_f32 v7, -v7, v10, v9
	v_div_fmas_f32 v7, v7, v8, v10
	v_div_fixup_f32 v5, v7, v6, v120
	ds_write_b32 v4, v5 offset:24576
	s_waitcnt vmcnt(2)
	v_mul_f32_e32 v6, 0xbfb8aa3b, v121
	v_exp_f32_e32 v6, v6
	s_nop 0
	v_add_f32_e32 v6, 1.0, v6
	v_div_scale_f32 v7, s[6:7], v6, v6, v121
	v_rcp_f32_e32 v8, v7
	v_div_scale_f32 v9, vcc, v121, v6, v121
	v_fma_f32 v10, -v7, v8, 1.0
	v_fmac_f32_e32 v8, v10, v8
	v_mul_f32_e32 v10, v9, v8
	v_fma_f32 v11, -v7, v10, v9
	v_fmac_f32_e32 v10, v11, v8
	v_fma_f32 v7, -v7, v10, v9
	v_div_fmas_f32 v7, v7, v8, v10
	v_div_fixup_f32 v5, v7, v6, v121
	ds_write_b32 v4, v5 offset:26624
	s_waitcnt vmcnt(1)
	v_mul_f32_e32 v6, 0xbfb8aa3b, v122
	v_exp_f32_e32 v6, v6
	s_nop 0
	v_add_f32_e32 v6, 1.0, v6
	v_div_scale_f32 v7, s[6:7], v6, v6, v122
	v_rcp_f32_e32 v8, v7
	v_div_scale_f32 v9, vcc, v122, v6, v122
	v_fma_f32 v10, -v7, v8, 1.0
	v_fmac_f32_e32 v8, v10, v8
	v_mul_f32_e32 v10, v9, v8
	v_fma_f32 v11, -v7, v10, v9
	v_fmac_f32_e32 v10, v11, v8
	v_fma_f32 v7, -v7, v10, v9
	v_div_fmas_f32 v7, v7, v8, v10
	v_div_fixup_f32 v5, v7, v6, v122
	ds_write_b32 v4, v5 offset:28672
	s_waitcnt vmcnt(0)
	v_mul_f32_e32 v6, 0xbfb8aa3b, v123
	v_exp_f32_e32 v6, v6
	s_nop 0
	v_add_f32_e32 v6, 1.0, v6
	v_div_scale_f32 v7, s[6:7], v6, v6, v123
	v_rcp_f32_e32 v8, v7
	v_div_scale_f32 v9, vcc, v123, v6, v123
	v_fma_f32 v10, -v7, v8, 1.0
	v_fmac_f32_e32 v8, v10, v8
	v_mul_f32_e32 v10, v9, v8
	v_fma_f32 v11, -v7, v10, v9
	v_fmac_f32_e32 v10, v11, v8
	v_fma_f32 v7, -v7, v10, v9
	v_div_fmas_f32 v7, v7, v8, v10
	v_div_fixup_f32 v5, v7, v6, v123
	ds_write_b32 v4, v5 offset:30720
